# conv-tile-loop-handwritten-depth3-prefetch
# speedup vs baseline: 1.0562x; 1.0039x over previous
.LBB0_268:
	s_or_b64 exec, exec, s[38:39]
	v_readfirstlane_b32 s46, v17
	v_readlane_b32 s47, v250, 14
	v_and_b32_e32 v2, 15, v128
	v_lshrrev_b32_e32 v3, 4, v128
	v_lshlrev_b32_e32 v4, 4, v2
	v_lshlrev_b32_e32 v5, 2, v2
	v_mul_u32_u24_e32 v6, 0x3820, v3
	v_lshlrev_b32_e32 v7, 2, v3
	v_lshl_add_u32 v8, v3, 12, v4
	v_add_u32_e32 v9, 0x20000, v8
	v_lshl_add_u32 v10, v3, 8, v4
	v_add_u32_e32 v11, 0x2000, v10
	v_lshrrev_b32_e32 v22, 3, v128
	v_and_b32_e32 v23, 7, v128
	v_lshlrev_b32_e32 v24, 4, v23
	v_lshl_add_u32 v12, v22, 11, v24
	v_lshl_add_u32 v13, v22, 7, v24
	v_mul_u32_u24_e32 v14, 0x104, v3
	v_add_u32_e32 v14, v14, v4
	v_add_u32_e32 v15, 0x2080, v14
	v_add_u32_e32 v16, 0x4100, v14
	v_add_u32_e32 v17, 0x4100, v15
	v_mul_u32_u24_e32 v18, 0x820, v23
	v_lshl_add_u32 v18, v22, 2, v18
	v_add_u32_e32 v19, 0x410, v18
	v_add_u32_e32 v20, 0x4100, v18
	v_add_u32_e32 v21, 0x4100, v19
	s_lshr_b32 s47, s47, 6
	s_add_i32 s34, s46, 0
	s_lshr_b32 s42, s34, 4
	s_and_b32 s43, s34, 15
	s_mul_i32 s44, s43, 0xe0800
	s_mul_i32 s45, s47, 0xe08000
	s_add_u32 s44, s44, s45
	s_add_u32 s0, s76, s44
	s_addc_u32 s1, s77, 0
	s_lshl_b32 s44, s47, 12
	s_lshl_b32 s45, s43, 8
	s_add_u32 s44, s44, s45
	s_add_u32 s4, s74, s44
	s_addc_u32 s5, s75, 0
	s_and_b32 s44, s42, 3
	s_lshl_b32 s44, s44, 6
	s_lshr_b32 s45, s42, 2
	s_cmp_ge_u32 s45, 8
	s_cselect_b32 s43, 8, 0
	s_lshl_b32 s45, s45, 8
	s_add_u32 s45, s45, s43
	v_add_u32_e32 v22, s44, v5
	v_lshrrev_b32_e32 v23, 2, v22
	v_and_b32_e32 v23, 32, v23
	v_lshlrev_b32_e32 v24, 1, v22
	v_and_b32_e32 v24, 0xc0, v24
	v_and_b32_e32 v22, 31, v22
	v_add3_u32 v22, v22, v23, v24
	v_add_u32_e32 v22, s45, v22
	v_lshl_add_u32 v26, v22, 2, v6
	v_add_u32_e32 v27, 0x70400, v26
	global_load_dwordx4 v[28:31], v26, s[0:1]
	global_load_dwordx4 v[32:35], v27, s[0:1]
	global_load_dword v36, v7, s[4:5]
	global_load_dword v37, v7, s[4:5] offset:128
	s_add_i32 s34, s46, 72
	s_lshr_b32 s42, s34, 4
	s_and_b32 s43, s34, 15
	s_mul_i32 s44, s43, 0xe0800
	s_mul_i32 s45, s47, 0xe08000
	s_add_u32 s44, s44, s45
	s_add_u32 s0, s76, s44
	s_addc_u32 s1, s77, 0
	s_lshl_b32 s44, s47, 12
	s_lshl_b32 s45, s43, 8
	s_add_u32 s44, s44, s45
	s_add_u32 s4, s74, s44
	s_addc_u32 s5, s75, 0
	s_and_b32 s44, s42, 3
	s_lshl_b32 s44, s44, 6
	s_lshr_b32 s45, s42, 2
	s_cmp_ge_u32 s45, 8
	s_cselect_b32 s43, 8, 0
	s_lshl_b32 s45, s45, 8
	s_add_u32 s45, s45, s43
	v_add_u32_e32 v22, s44, v5
	v_lshrrev_b32_e32 v23, 2, v22
	v_and_b32_e32 v23, 32, v23
	v_lshlrev_b32_e32 v24, 1, v22
	v_and_b32_e32 v24, 0xc0, v24
	v_and_b32_e32 v22, 31, v22
	v_add3_u32 v22, v22, v23, v24
	v_add_u32_e32 v22, s45, v22
	v_lshl_add_u32 v26, v22, 2, v6
	v_add_u32_e32 v27, 0x70400, v26
	global_load_dwordx4 v[40:43], v26, s[0:1]
	global_load_dwordx4 v[44:47], v27, s[0:1]
	global_load_dword v48, v7, s[4:5]
	global_load_dword v49, v7, s[4:5] offset:128
	s_add_i32 s34, s46, 144
	s_lshr_b32 s42, s34, 4
	s_and_b32 s43, s34, 15
	s_mul_i32 s44, s43, 0xe0800
	s_mul_i32 s45, s47, 0xe08000
	s_add_u32 s44, s44, s45
	s_add_u32 s0, s76, s44
	s_addc_u32 s1, s77, 0
	s_lshl_b32 s44, s47, 12
	s_lshl_b32 s45, s43, 8
	s_add_u32 s44, s44, s45
	s_add_u32 s4, s74, s44
	s_addc_u32 s5, s75, 0
	s_and_b32 s44, s42, 3
	s_lshl_b32 s44, s44, 6
	s_lshr_b32 s45, s42, 2
	s_cmp_ge_u32 s45, 8
	s_cselect_b32 s43, 8, 0
	s_lshl_b32 s45, s45, 8
	s_add_u32 s45, s45, s43
	v_add_u32_e32 v22, s44, v5
	v_lshrrev_b32_e32 v23, 2, v22
	v_and_b32_e32 v23, 32, v23
	v_lshlrev_b32_e32 v24, 1, v22
	v_and_b32_e32 v24, 0xc0, v24
	v_and_b32_e32 v22, 31, v22
	v_add3_u32 v22, v22, v23, v24
	v_add_u32_e32 v22, s45, v22
	v_lshl_add_u32 v26, v22, 2, v6
	v_add_u32_e32 v27, 0x70400, v26
	global_load_dwordx4 v[52:55], v26, s[0:1]
	global_load_dwordx4 v[56:59], v27, s[0:1]
	global_load_dword v60, v7, s[4:5]
	global_load_dword v61, v7, s[4:5] offset:128
	s_add_i32 s34, s46, 216
	s_lshr_b32 s42, s34, 4
	s_and_b32 s43, s34, 15
	s_mul_i32 s44, s43, 0xe0800
	s_mul_i32 s45, s47, 0xe08000
	s_add_u32 s44, s44, s45
	s_add_u32 s0, s76, s44
	s_addc_u32 s1, s77, 0
	s_lshl_b32 s44, s47, 12
	s_lshl_b32 s45, s43, 8
	s_add_u32 s44, s44, s45
	s_add_u32 s4, s74, s44
	s_addc_u32 s5, s75, 0
	s_and_b32 s44, s42, 3
	s_lshl_b32 s44, s44, 6
	s_lshr_b32 s45, s42, 2
	s_cmp_ge_u32 s45, 8
	s_cselect_b32 s43, 8, 0
	s_lshl_b32 s45, s45, 8
	s_add_u32 s45, s45, s43
	v_add_u32_e32 v22, s44, v5
	v_lshrrev_b32_e32 v23, 2, v22
	v_and_b32_e32 v23, 32, v23
	v_lshlrev_b32_e32 v24, 1, v22
	v_and_b32_e32 v24, 0xc0, v24
	v_and_b32_e32 v22, 31, v22
	v_add3_u32 v22, v22, v23, v24
	v_add_u32_e32 v22, s45, v22
	v_lshl_add_u32 v26, v22, 2, v6
	v_add_u32_e32 v27, 0x70400, v26
	global_load_dwordx4 v[64:67], v26, s[0:1]
	global_load_dwordx4 v[68:71], v27, s[0:1]
	global_load_dword v72, v7, s[4:5]
	global_load_dword v73, v7, s[4:5] offset:128
	s_waitcnt vmcnt(12)
	s_add_i32 s34, s46, 0
	s_lshr_b32 s42, s34, 4
	s_and_b32 s43, s34, 15
	s_mul_i32 s44, s47, 0x700000
	s_lshl_b32 s45, s42, 17
	s_add_u32 s44, s44, s45
	s_lshl_b32 s45, s43, 7
	s_add_u32 s44, s44, s45
	s_add_u32 s44, s44, 0x8000
	s_add_u32 s36, s70, s44
	s_addc_u32 s37, s71, 0
	v_mul_f32_e32 v28, v28, v36
	v_mul_f32_e32 v29, v29, v36
	v_mul_f32_e32 v30, v30, v36
	v_mul_f32_e32 v31, v31, v36
	v_mul_f32_e32 v32, v32, v37
	v_mul_f32_e32 v33, v33, v37
	v_mul_f32_e32 v34, v34, v37
	v_mul_f32_e32 v35, v35, v37
	ds_write2_b32 v14, v28, v29 offset1:1
	ds_write2_b32 v14, v30, v31 offset0:2 offset1:3
	ds_write2_b32 v15, v32, v33 offset1:1
	ds_write2_b32 v15, v34, v35 offset0:2 offset1:3
	s_waitcnt lgkmcnt(0)
	s_barrier
	ds_read2_b32 v[76:77], v18 offset1:65
	ds_read2_b32 v[78:79], v18 offset0:130 offset1:195
	ds_read2_b32 v[80:81], v19 offset1:65
	ds_read2_b32 v[82:83], v19 offset0:130 offset1:195
	s_waitcnt lgkmcnt(0)
	v_cvt_pk_bf16_f32 v84, v76, v77
	v_cvt_pk_bf16_f32 v85, v78, v79
	v_cvt_pk_bf16_f32 v86, v80, v81
	v_cvt_pk_bf16_f32 v87, v82, v83
	global_store_dwordx4 v12, v[84:87], s[36:37]
	s_add_i32 s34, s46, 288
	s_lshr_b32 s42, s34, 4
	s_and_b32 s43, s34, 15
	s_mul_i32 s44, s43, 0xe0800
	s_mul_i32 s45, s47, 0xe08000
	s_add_u32 s44, s44, s45
	s_add_u32 s0, s76, s44
	s_addc_u32 s1, s77, 0
	s_lshl_b32 s44, s47, 12
	s_lshl_b32 s45, s43, 8
	s_add_u32 s44, s44, s45
	s_add_u32 s4, s74, s44
	s_addc_u32 s5, s75, 0
	s_and_b32 s44, s42, 3
	s_lshl_b32 s44, s44, 6
	s_lshr_b32 s45, s42, 2
	s_cmp_ge_u32 s45, 8
	s_cselect_b32 s43, 8, 0
	s_lshl_b32 s45, s45, 8
	s_add_u32 s45, s45, s43
	v_add_u32_e32 v22, s44, v5
	v_lshrrev_b32_e32 v23, 2, v22
	v_and_b32_e32 v23, 32, v23
	v_lshlrev_b32_e32 v24, 1, v22
	v_and_b32_e32 v24, 0xc0, v24
	v_and_b32_e32 v22, 31, v22
	v_add3_u32 v22, v22, v23, v24
	v_add_u32_e32 v22, s45, v22
	v_lshl_add_u32 v26, v22, 2, v6
	v_add_u32_e32 v27, 0x70400, v26
	global_load_dwordx4 v[28:31], v26, s[0:1]
	global_load_dwordx4 v[32:35], v27, s[0:1]
	global_load_dword v36, v7, s[4:5]
	global_load_dword v37, v7, s[4:5] offset:128
	s_waitcnt vmcnt(13)
	s_add_i32 s34, s46, 72
	s_lshr_b32 s42, s34, 4
	s_and_b32 s43, s34, 15
	s_mul_i32 s44, s47, 0x700000
	s_lshl_b32 s45, s42, 17
	s_add_u32 s44, s44, s45
	s_lshl_b32 s45, s43, 7
	s_add_u32 s44, s44, s45
	s_add_u32 s44, s44, 0x8000
	s_add_u32 s36, s70, s44
	s_addc_u32 s37, s71, 0
	v_mul_f32_e32 v40, v40, v48
	v_mul_f32_e32 v41, v41, v48
	v_mul_f32_e32 v42, v42, v48
	v_mul_f32_e32 v43, v43, v48
	v_mul_f32_e32 v44, v44, v49
	v_mul_f32_e32 v45, v45, v49
	v_mul_f32_e32 v46, v46, v49
	v_mul_f32_e32 v47, v47, v49
	ds_write2_b32 v16, v40, v41 offset1:1
	ds_write2_b32 v16, v42, v43 offset0:2 offset1:3
	ds_write2_b32 v17, v44, v45 offset1:1
	ds_write2_b32 v17, v46, v47 offset0:2 offset1:3
	s_waitcnt lgkmcnt(0)
	s_barrier
	ds_read2_b32 v[76:77], v20 offset1:65
	ds_read2_b32 v[78:79], v20 offset0:130 offset1:195
	ds_read2_b32 v[80:81], v21 offset1:65
	ds_read2_b32 v[82:83], v21 offset0:130 offset1:195
	s_waitcnt lgkmcnt(0)
	v_cvt_pk_bf16_f32 v88, v76, v77
	v_cvt_pk_bf16_f32 v89, v78, v79
	v_cvt_pk_bf16_f32 v90, v80, v81
	v_cvt_pk_bf16_f32 v91, v82, v83
	global_store_dwordx4 v12, v[88:91], s[36:37]
	s_add_i32 s34, s46, 360
	s_lshr_b32 s42, s34, 4
	s_and_b32 s43, s34, 15
	s_mul_i32 s44, s43, 0xe0800
	s_mul_i32 s45, s47, 0xe08000
	s_add_u32 s44, s44, s45
	s_add_u32 s0, s76, s44
	s_addc_u32 s1, s77, 0
	s_lshl_b32 s44, s47, 12
	s_lshl_b32 s45, s43, 8
	s_add_u32 s44, s44, s45
	s_add_u32 s4, s74, s44
	s_addc_u32 s5, s75, 0
	s_and_b32 s44, s42, 3
	s_lshl_b32 s44, s44, 6
	s_lshr_b32 s45, s42, 2
	s_cmp_ge_u32 s45, 8
	s_cselect_b32 s43, 8, 0
	s_lshl_b32 s45, s45, 8
	s_add_u32 s45, s45, s43
	v_add_u32_e32 v22, s44, v5
	v_lshrrev_b32_e32 v23, 2, v22
	v_and_b32_e32 v23, 32, v23
	v_lshlrev_b32_e32 v24, 1, v22
	v_and_b32_e32 v24, 0xc0, v24
	v_and_b32_e32 v22, 31, v22
	v_add3_u32 v22, v22, v23, v24
	v_add_u32_e32 v22, s45, v22
	v_lshl_add_u32 v26, v22, 2, v6
	v_add_u32_e32 v27, 0x70400, v26
	global_load_dwordx4 v[40:43], v26, s[0:1]
	global_load_dwordx4 v[44:47], v27, s[0:1]
	global_load_dword v48, v7, s[4:5]
	global_load_dword v49, v7, s[4:5] offset:128
	s_waitcnt vmcnt(14)
	s_add_i32 s34, s46, 144
	s_lshr_b32 s42, s34, 4
	s_and_b32 s43, s34, 15
	s_mul_i32 s44, s47, 0x700000
	s_lshl_b32 s45, s42, 17
	s_add_u32 s44, s44, s45
	s_lshl_b32 s45, s43, 7
	s_add_u32 s44, s44, s45
	s_add_u32 s44, s44, 0x8000
	s_add_u32 s36, s70, s44
	s_addc_u32 s37, s71, 0
	v_mul_f32_e32 v52, v52, v60
	v_mul_f32_e32 v53, v53, v60
	v_mul_f32_e32 v54, v54, v60
	v_mul_f32_e32 v55, v55, v60
	v_mul_f32_e32 v56, v56, v61
	v_mul_f32_e32 v57, v57, v61
	v_mul_f32_e32 v58, v58, v61
	v_mul_f32_e32 v59, v59, v61
	ds_write2_b32 v14, v52, v53 offset1:1
	ds_write2_b32 v14, v54, v55 offset0:2 offset1:3
	ds_write2_b32 v15, v56, v57 offset1:1
	ds_write2_b32 v15, v58, v59 offset0:2 offset1:3
	s_waitcnt lgkmcnt(0)
	s_barrier
	ds_read2_b32 v[76:77], v18 offset1:65
	ds_read2_b32 v[78:79], v18 offset0:130 offset1:195
	ds_read2_b32 v[80:81], v19 offset1:65
	ds_read2_b32 v[82:83], v19 offset0:130 offset1:195
	s_waitcnt lgkmcnt(0)
	v_cvt_pk_bf16_f32 v84, v76, v77
	v_cvt_pk_bf16_f32 v85, v78, v79
	v_cvt_pk_bf16_f32 v86, v80, v81
	v_cvt_pk_bf16_f32 v87, v82, v83
	global_store_dwordx4 v12, v[84:87], s[36:37]
	s_add_i32 s34, s46, 432
	s_lshr_b32 s42, s34, 4
	s_and_b32 s43, s34, 15
	s_mul_i32 s44, s43, 0xe0800
	s_mul_i32 s45, s47, 0xe08000
	s_add_u32 s44, s44, s45
	s_add_u32 s0, s76, s44
	s_addc_u32 s1, s77, 0
	s_lshl_b32 s44, s47, 12
	s_lshl_b32 s45, s43, 8
	s_add_u32 s44, s44, s45
	s_add_u32 s4, s74, s44
	s_addc_u32 s5, s75, 0
	s_and_b32 s44, s42, 3
	s_lshl_b32 s44, s44, 6
	s_lshr_b32 s45, s42, 2
	s_cmp_ge_u32 s45, 8
	s_cselect_b32 s43, 8, 0
	s_lshl_b32 s45, s45, 8
	s_add_u32 s45, s45, s43
	v_add_u32_e32 v22, s44, v5
	v_lshrrev_b32_e32 v23, 2, v22
	v_and_b32_e32 v23, 32, v23
	v_lshlrev_b32_e32 v24, 1, v22
	v_and_b32_e32 v24, 0xc0, v24
	v_and_b32_e32 v22, 31, v22
	v_add3_u32 v22, v22, v23, v24
	v_add_u32_e32 v22, s45, v22
	v_lshl_add_u32 v26, v22, 2, v6
	v_add_u32_e32 v27, 0x70400, v26
	global_load_dwordx4 v[52:55], v26, s[0:1]
	global_load_dwordx4 v[56:59], v27, s[0:1]
	global_load_dword v60, v7, s[4:5]
	global_load_dword v61, v7, s[4:5] offset:128
	s_waitcnt vmcnt(15)
	s_add_i32 s34, s46, 216
	s_lshr_b32 s42, s34, 4
	s_and_b32 s43, s34, 15
	s_mul_i32 s44, s47, 0x700000
	s_lshl_b32 s45, s42, 17
	s_add_u32 s44, s44, s45
	s_lshl_b32 s45, s43, 7
	s_add_u32 s44, s44, s45
	s_add_u32 s44, s44, 0x8000
	s_add_u32 s36, s70, s44
	s_addc_u32 s37, s71, 0
	v_mul_f32_e32 v64, v64, v72
	v_mul_f32_e32 v65, v65, v72
	v_mul_f32_e32 v66, v66, v72
	v_mul_f32_e32 v67, v67, v72
	v_mul_f32_e32 v68, v68, v73
	v_mul_f32_e32 v69, v69, v73
	v_mul_f32_e32 v70, v70, v73
	v_mul_f32_e32 v71, v71, v73
	ds_write2_b32 v16, v64, v65 offset1:1
	ds_write2_b32 v16, v66, v67 offset0:2 offset1:3
	ds_write2_b32 v17, v68, v69 offset1:1
	ds_write2_b32 v17, v70, v71 offset0:2 offset1:3
	s_waitcnt lgkmcnt(0)
	s_barrier
	ds_read2_b32 v[76:77], v20 offset1:65
	ds_read2_b32 v[78:79], v20 offset0:130 offset1:195
	ds_read2_b32 v[80:81], v21 offset1:65
	ds_read2_b32 v[82:83], v21 offset0:130 offset1:195
	s_waitcnt lgkmcnt(0)
	v_cvt_pk_bf16_f32 v88, v76, v77
	v_cvt_pk_bf16_f32 v89, v78, v79
	v_cvt_pk_bf16_f32 v90, v80, v81
	v_cvt_pk_bf16_f32 v91, v82, v83
	global_store_dwordx4 v12, v[88:91], s[36:37]
	s_add_i32 s34, s46, 504
	s_lshr_b32 s42, s34, 4
	s_and_b32 s43, s34, 15
	s_mul_i32 s44, s43, 0xe0800
	s_mul_i32 s45, s47, 0xe08000
	s_add_u32 s44, s44, s45
	s_add_u32 s0, s76, s44
	s_addc_u32 s1, s77, 0
	s_lshl_b32 s44, s47, 12
	s_lshl_b32 s45, s43, 8
	s_add_u32 s44, s44, s45
	s_add_u32 s4, s74, s44
	s_addc_u32 s5, s75, 0
	s_and_b32 s44, s42, 3
	s_lshl_b32 s44, s44, 6
	s_lshr_b32 s45, s42, 2
	s_cmp_ge_u32 s45, 8
	s_cselect_b32 s43, 8, 0
	s_lshl_b32 s45, s45, 8
	s_add_u32 s45, s45, s43
	v_add_u32_e32 v22, s44, v5
	v_lshrrev_b32_e32 v23, 2, v22
	v_and_b32_e32 v23, 32, v23
	v_lshlrev_b32_e32 v24, 1, v22
	v_and_b32_e32 v24, 0xc0, v24
	v_and_b32_e32 v22, 31, v22
	v_add3_u32 v22, v22, v23, v24
	v_add_u32_e32 v22, s45, v22
	v_lshl_add_u32 v26, v22, 2, v6
	v_add_u32_e32 v27, 0x70400, v26
	global_load_dwordx4 v[64:67], v26, s[0:1]
	global_load_dwordx4 v[68:71], v27, s[0:1]
	global_load_dword v72, v7, s[4:5]
	global_load_dword v73, v7, s[4:5] offset:128
	s_waitcnt vmcnt(15)
	s_add_i32 s34, s46, 288
	s_lshr_b32 s42, s34, 4
	s_and_b32 s43, s34, 15
	s_mul_i32 s44, s47, 0x700000
	s_lshl_b32 s45, s42, 17
	s_add_u32 s44, s44, s45
	s_lshl_b32 s45, s43, 7
	s_add_u32 s44, s44, s45
	s_add_u32 s44, s44, 0x8000
	s_add_u32 s36, s70, s44
	s_addc_u32 s37, s71, 0
	v_mul_f32_e32 v28, v28, v36
	v_mul_f32_e32 v29, v29, v36
	v_mul_f32_e32 v30, v30, v36
	v_mul_f32_e32 v31, v31, v36
	v_mul_f32_e32 v32, v32, v37
	v_mul_f32_e32 v33, v33, v37
	v_mul_f32_e32 v34, v34, v37
	v_mul_f32_e32 v35, v35, v37
	ds_write2_b32 v14, v28, v29 offset1:1
	ds_write2_b32 v14, v30, v31 offset0:2 offset1:3
	ds_write2_b32 v15, v32, v33 offset1:1
	ds_write2_b32 v15, v34, v35 offset0:2 offset1:3
	s_waitcnt lgkmcnt(0)
	s_barrier
	ds_read2_b32 v[76:77], v18 offset1:65
	ds_read2_b32 v[78:79], v18 offset0:130 offset1:195
	ds_read2_b32 v[80:81], v19 offset1:65
	ds_read2_b32 v[82:83], v19 offset0:130 offset1:195
	s_waitcnt lgkmcnt(0)
	v_cvt_pk_bf16_f32 v84, v76, v77
	v_cvt_pk_bf16_f32 v85, v78, v79
	v_cvt_pk_bf16_f32 v86, v80, v81
	v_cvt_pk_bf16_f32 v87, v82, v83
	global_store_dwordx4 v12, v[84:87], s[36:37]
	s_add_i32 s34, s46, 576
	s_lshr_b32 s42, s34, 4
	s_and_b32 s43, s34, 15
	s_mul_i32 s44, s43, 0xe0800
	s_mul_i32 s45, s47, 0xe08000
	s_add_u32 s44, s44, s45
	s_add_u32 s0, s76, s44
	s_addc_u32 s1, s77, 0
	s_lshl_b32 s44, s47, 12
	s_lshl_b32 s45, s43, 8
	s_add_u32 s44, s44, s45
	s_add_u32 s4, s74, s44
	s_addc_u32 s5, s75, 0
	s_and_b32 s44, s42, 3
	s_lshl_b32 s44, s44, 6
	s_lshr_b32 s45, s42, 2
	s_cmp_ge_u32 s45, 8
	s_cselect_b32 s43, 8, 0
	s_lshl_b32 s45, s45, 8
	s_add_u32 s45, s45, s43
	v_add_u32_e32 v22, s44, v5
	v_lshrrev_b32_e32 v23, 2, v22
	v_and_b32_e32 v23, 32, v23
	v_lshlrev_b32_e32 v24, 1, v22
	v_and_b32_e32 v24, 0xc0, v24
	v_and_b32_e32 v22, 31, v22
	v_add3_u32 v22, v22, v23, v24
	v_add_u32_e32 v22, s45, v22
	v_lshl_add_u32 v26, v22, 2, v6
	v_add_u32_e32 v27, 0x70400, v26
	global_load_dwordx4 v[28:31], v26, s[0:1]
	global_load_dwordx4 v[32:35], v27, s[0:1]
	global_load_dword v36, v7, s[4:5]
	global_load_dword v37, v7, s[4:5] offset:128
	s_waitcnt vmcnt(15)
	s_add_i32 s34, s46, 360
	s_lshr_b32 s42, s34, 4
	s_and_b32 s43, s34, 15
	s_mul_i32 s44, s47, 0x700000
	s_lshl_b32 s45, s42, 17
	s_add_u32 s44, s44, s45
	s_lshl_b32 s45, s43, 7
	s_add_u32 s44, s44, s45
	s_add_u32 s44, s44, 0x8000
	s_add_u32 s36, s70, s44
	s_addc_u32 s37, s71, 0
	v_mul_f32_e32 v40, v40, v48
	v_mul_f32_e32 v41, v41, v48
	v_mul_f32_e32 v42, v42, v48
	v_mul_f32_e32 v43, v43, v48
	v_mul_f32_e32 v44, v44, v49
	v_mul_f32_e32 v45, v45, v49
	v_mul_f32_e32 v46, v46, v49
	v_mul_f32_e32 v47, v47, v49
	ds_write2_b32 v16, v40, v41 offset1:1
	ds_write2_b32 v16, v42, v43 offset0:2 offset1:3
	ds_write2_b32 v17, v44, v45 offset1:1
	ds_write2_b32 v17, v46, v47 offset0:2 offset1:3
	s_waitcnt lgkmcnt(0)
	s_barrier
	ds_read2_b32 v[76:77], v20 offset1:65
	ds_read2_b32 v[78:79], v20 offset0:130 offset1:195
	ds_read2_b32 v[80:81], v21 offset1:65
	ds_read2_b32 v[82:83], v21 offset0:130 offset1:195
	s_waitcnt lgkmcnt(0)
	v_cvt_pk_bf16_f32 v88, v76, v77
	v_cvt_pk_bf16_f32 v89, v78, v79
	v_cvt_pk_bf16_f32 v90, v80, v81
	v_cvt_pk_bf16_f32 v91, v82, v83
	global_store_dwordx4 v12, v[88:91], s[36:37]
	s_add_i32 s34, s46, 648
	s_lshr_b32 s42, s34, 4
	s_and_b32 s43, s34, 15
	s_mul_i32 s44, s43, 0xe0800
	s_mul_i32 s45, s47, 0xe08000
	s_add_u32 s44, s44, s45
	s_add_u32 s0, s76, s44
	s_addc_u32 s1, s77, 0
	s_lshl_b32 s44, s47, 12
	s_lshl_b32 s45, s43, 8
	s_add_u32 s44, s44, s45
	s_add_u32 s4, s74, s44
	s_addc_u32 s5, s75, 0
	s_and_b32 s44, s42, 3
	s_lshl_b32 s44, s44, 6
	s_lshr_b32 s45, s42, 2
	s_cmp_ge_u32 s45, 8
	s_cselect_b32 s43, 8, 0
	s_lshl_b32 s45, s45, 8
	s_add_u32 s45, s45, s43
	v_add_u32_e32 v22, s44, v5
	v_lshrrev_b32_e32 v23, 2, v22
	v_and_b32_e32 v23, 32, v23
	v_lshlrev_b32_e32 v24, 1, v22
	v_and_b32_e32 v24, 0xc0, v24
	v_and_b32_e32 v22, 31, v22
	v_add3_u32 v22, v22, v23, v24
	v_add_u32_e32 v22, s45, v22
	v_lshl_add_u32 v26, v22, 2, v6
	v_add_u32_e32 v27, 0x70400, v26
	global_load_dwordx4 v[40:43], v26, s[0:1]
	global_load_dwordx4 v[44:47], v27, s[0:1]
	global_load_dword v48, v7, s[4:5]
	global_load_dword v49, v7, s[4:5] offset:128
	s_waitcnt vmcnt(15)
	s_add_i32 s34, s46, 432
	s_lshr_b32 s42, s34, 4
	s_and_b32 s43, s34, 15
	s_mul_i32 s44, s47, 0x700000
	s_lshl_b32 s45, s42, 17
	s_add_u32 s44, s44, s45
	s_lshl_b32 s45, s43, 7
	s_add_u32 s44, s44, s45
	s_add_u32 s44, s44, 0x8000
	s_add_u32 s36, s70, s44
	s_addc_u32 s37, s71, 0
	v_mul_f32_e32 v52, v52, v60
	v_mul_f32_e32 v53, v53, v60
	v_mul_f32_e32 v54, v54, v60
	v_mul_f32_e32 v55, v55, v60
	v_mul_f32_e32 v56, v56, v61
	v_mul_f32_e32 v57, v57, v61
	v_mul_f32_e32 v58, v58, v61
	v_mul_f32_e32 v59, v59, v61
	ds_write2_b32 v14, v52, v53 offset1:1
	ds_write2_b32 v14, v54, v55 offset0:2 offset1:3
	ds_write2_b32 v15, v56, v57 offset1:1
	ds_write2_b32 v15, v58, v59 offset0:2 offset1:3
	s_waitcnt lgkmcnt(0)
	s_barrier
	ds_read2_b32 v[76:77], v18 offset1:65
	ds_read2_b32 v[78:79], v18 offset0:130 offset1:195
	ds_read2_b32 v[80:81], v19 offset1:65
	ds_read2_b32 v[82:83], v19 offset0:130 offset1:195
	s_waitcnt lgkmcnt(0)
	v_cvt_pk_bf16_f32 v84, v76, v77
	v_cvt_pk_bf16_f32 v85, v78, v79
	v_cvt_pk_bf16_f32 v86, v80, v81
	v_cvt_pk_bf16_f32 v87, v82, v83
	global_store_dwordx4 v12, v[84:87], s[36:37]
	s_add_i32 s34, s46, 720
	s_lshr_b32 s42, s34, 4
	s_and_b32 s43, s34, 15
	s_mul_i32 s44, s43, 0xe0800
	s_mul_i32 s45, s47, 0xe08000
	s_add_u32 s44, s44, s45
	s_add_u32 s0, s76, s44
	s_addc_u32 s1, s77, 0
	s_lshl_b32 s44, s47, 12
	s_lshl_b32 s45, s43, 8
	s_add_u32 s44, s44, s45
	s_add_u32 s4, s74, s44
	s_addc_u32 s5, s75, 0
	s_and_b32 s44, s42, 3
	s_lshl_b32 s44, s44, 6
	s_lshr_b32 s45, s42, 2
	s_cmp_ge_u32 s45, 8
	s_cselect_b32 s43, 8, 0
	s_lshl_b32 s45, s45, 8
	s_add_u32 s45, s45, s43
	v_add_u32_e32 v22, s44, v5
	v_lshrrev_b32_e32 v23, 2, v22
	v_and_b32_e32 v23, 32, v23
	v_lshlrev_b32_e32 v24, 1, v22
	v_and_b32_e32 v24, 0xc0, v24
	v_and_b32_e32 v22, 31, v22
	v_add3_u32 v22, v22, v23, v24
	v_add_u32_e32 v22, s45, v22
	v_lshl_add_u32 v26, v22, 2, v6
	v_add_u32_e32 v27, 0x70400, v26
	global_load_dwordx4 v[52:55], v26, s[0:1]
	global_load_dwordx4 v[56:59], v27, s[0:1]
	global_load_dword v60, v7, s[4:5]
	global_load_dword v61, v7, s[4:5] offset:128
	s_waitcnt vmcnt(15)
	s_add_i32 s34, s46, 504
	s_lshr_b32 s42, s34, 4
	s_and_b32 s43, s34, 15
	s_mul_i32 s44, s47, 0x700000
	s_lshl_b32 s45, s42, 17
	s_add_u32 s44, s44, s45
	s_lshl_b32 s45, s43, 7
	s_add_u32 s44, s44, s45
	s_add_u32 s44, s44, 0x8000
	s_add_u32 s36, s70, s44
	s_addc_u32 s37, s71, 0
	v_mul_f32_e32 v64, v64, v72
	v_mul_f32_e32 v65, v65, v72
	v_mul_f32_e32 v66, v66, v72
	v_mul_f32_e32 v67, v67, v72
	v_mul_f32_e32 v68, v68, v73
	v_mul_f32_e32 v69, v69, v73
	v_mul_f32_e32 v70, v70, v73
	v_mul_f32_e32 v71, v71, v73
	ds_write2_b32 v16, v64, v65 offset1:1
	ds_write2_b32 v16, v66, v67 offset0:2 offset1:3
	ds_write2_b32 v17, v68, v69 offset1:1
	ds_write2_b32 v17, v70, v71 offset0:2 offset1:3
	s_waitcnt lgkmcnt(0)
	s_barrier
	ds_read2_b32 v[76:77], v20 offset1:65
	ds_read2_b32 v[78:79], v20 offset0:130 offset1:195
	ds_read2_b32 v[80:81], v21 offset1:65
	ds_read2_b32 v[82:83], v21 offset0:130 offset1:195
	s_waitcnt lgkmcnt(0)
	v_cvt_pk_bf16_f32 v88, v76, v77
	v_cvt_pk_bf16_f32 v89, v78, v79
	v_cvt_pk_bf16_f32 v90, v80, v81
	v_cvt_pk_bf16_f32 v91, v82, v83
	global_store_dwordx4 v12, v[88:91], s[36:37]
	s_add_i32 s34, s46, 792
	s_lshr_b32 s42, s34, 4
	s_and_b32 s43, s34, 15
	s_mul_i32 s44, s43, 0xe0800
	s_mul_i32 s45, s47, 0xe08000
	s_add_u32 s44, s44, s45
	s_add_u32 s0, s76, s44
	s_addc_u32 s1, s77, 0
	s_lshl_b32 s44, s47, 12
	s_lshl_b32 s45, s43, 8
	s_add_u32 s44, s44, s45
	s_add_u32 s4, s74, s44
	s_addc_u32 s5, s75, 0
	s_and_b32 s44, s42, 3
	s_lshl_b32 s44, s44, 6
	s_lshr_b32 s45, s42, 2
	s_cmp_ge_u32 s45, 8
	s_cselect_b32 s43, 8, 0
	s_lshl_b32 s45, s45, 8
	s_add_u32 s45, s45, s43
	v_add_u32_e32 v22, s44, v5
	v_lshrrev_b32_e32 v23, 2, v22
	v_and_b32_e32 v23, 32, v23
	v_lshlrev_b32_e32 v24, 1, v22
	v_and_b32_e32 v24, 0xc0, v24
	v_and_b32_e32 v22, 31, v22
	v_add3_u32 v22, v22, v23, v24
	v_add_u32_e32 v22, s45, v22
	v_lshl_add_u32 v26, v22, 2, v6
	v_add_u32_e32 v27, 0x70400, v26
	global_load_dwordx4 v[64:67], v26, s[0:1]
	global_load_dwordx4 v[68:71], v27, s[0:1]
	global_load_dword v72, v7, s[4:5]
	global_load_dword v73, v7, s[4:5] offset:128
	s_waitcnt vmcnt(15)
	s_add_i32 s34, s46, 576
	s_lshr_b32 s42, s34, 4
	s_and_b32 s43, s34, 15
	s_mul_i32 s44, s47, 0x700000
	s_lshl_b32 s45, s42, 17
	s_add_u32 s44, s44, s45
	s_lshl_b32 s45, s43, 7
	s_add_u32 s44, s44, s45
	s_add_u32 s44, s44, 0x8000
	s_add_u32 s36, s70, s44
	s_addc_u32 s37, s71, 0
	v_mul_f32_e32 v28, v28, v36
	v_mul_f32_e32 v29, v29, v36
	v_mul_f32_e32 v30, v30, v36
	v_mul_f32_e32 v31, v31, v36
	v_mul_f32_e32 v32, v32, v37
	v_mul_f32_e32 v33, v33, v37
	v_mul_f32_e32 v34, v34, v37
	v_mul_f32_e32 v35, v35, v37
	ds_write2_b32 v14, v28, v29 offset1:1
	ds_write2_b32 v14, v30, v31 offset0:2 offset1:3
	ds_write2_b32 v15, v32, v33 offset1:1
	ds_write2_b32 v15, v34, v35 offset0:2 offset1:3
	s_waitcnt lgkmcnt(0)
	s_barrier
	ds_read2_b32 v[76:77], v18 offset1:65
	ds_read2_b32 v[78:79], v18 offset0:130 offset1:195
	ds_read2_b32 v[80:81], v19 offset1:65
	ds_read2_b32 v[82:83], v19 offset0:130 offset1:195
	s_waitcnt lgkmcnt(0)
	v_cvt_pk_bf16_f32 v84, v76, v77
	v_cvt_pk_bf16_f32 v85, v78, v79
	v_cvt_pk_bf16_f32 v86, v80, v81
	v_cvt_pk_bf16_f32 v87, v82, v83
	global_store_dwordx4 v12, v[84:87], s[36:37]
	s_cmp_lt_u32 s46, 32
	s_cbranch_scc0 .Lconv_i12b
	s_add_i32 s34, s46, 864
	s_lshr_b32 s42, s34, 4
	s_and_b32 s43, s34, 15
	s_mul_i32 s44, s43, 0xe0800
	s_mul_i32 s45, s47, 0xe08000
	s_add_u32 s44, s44, s45
	s_add_u32 s0, s76, s44
	s_addc_u32 s1, s77, 0
	s_lshl_b32 s44, s47, 12
	s_lshl_b32 s45, s43, 8
	s_add_u32 s44, s44, s45
	s_add_u32 s4, s74, s44
	s_addc_u32 s5, s75, 0
	s_and_b32 s44, s42, 3
	s_lshl_b32 s44, s44, 6
	s_lshr_b32 s45, s42, 2
	s_cmp_ge_u32 s45, 8
	s_cselect_b32 s43, 8, 0
	s_lshl_b32 s45, s45, 8
	s_add_u32 s45, s45, s43
	v_add_u32_e32 v22, s44, v5
	v_lshrrev_b32_e32 v23, 2, v22
	v_and_b32_e32 v23, 32, v23
	v_lshlrev_b32_e32 v24, 1, v22
	v_and_b32_e32 v24, 0xc0, v24
	v_and_b32_e32 v22, 31, v22
	v_add3_u32 v22, v22, v23, v24
	v_add_u32_e32 v22, s45, v22
	v_lshl_add_u32 v26, v22, 2, v6
	v_add_u32_e32 v27, 0x70400, v26
	global_load_dwordx4 v[28:31], v26, s[0:1]
	global_load_dwordx4 v[32:35], v27, s[0:1]
	global_load_dword v36, v7, s[4:5]
	global_load_dword v37, v7, s[4:5] offset:128
	s_branch .Lconv_i12d
.Lconv_i12b:
	s_add_i32 s34, s46, -32
	s_lshr_b32 s42, s34, 4
	s_and_b32 s43, s34, 15
	s_lshl_b32 s44, s47, 22
	s_lshl_b32 s45, s43, 18
	s_add_u32 s44, s44, s45
	s_lshl_b32 s45, s42, 8
	s_add_u32 s44, s44, s45
	s_add_u32 s0, s88, s44
	s_addc_u32 s1, s89, 0
	global_load_dwordx4 v[28:31], v8, s[0:1]
	global_load_dwordx4 v[32:35], v9, s[0:1]
	global_load_dword v36, v7, s[74:75]
	global_load_dword v37, v7, s[74:75] offset:128
.Lconv_i12d:
	s_waitcnt vmcnt(15)
	s_add_i32 s34, s46, 648
	s_lshr_b32 s42, s34, 4
	s_and_b32 s43, s34, 15
	s_mul_i32 s44, s47, 0x700000
	s_lshl_b32 s45, s42, 17
	s_add_u32 s44, s44, s45
	s_lshl_b32 s45, s43, 7
	s_add_u32 s44, s44, s45
	s_add_u32 s44, s44, 0x8000
	s_add_u32 s36, s70, s44
	s_addc_u32 s37, s71, 0
	v_mul_f32_e32 v40, v40, v48
	v_mul_f32_e32 v41, v41, v48
	v_mul_f32_e32 v42, v42, v48
	v_mul_f32_e32 v43, v43, v48
	v_mul_f32_e32 v44, v44, v49
	v_mul_f32_e32 v45, v45, v49
	v_mul_f32_e32 v46, v46, v49
	v_mul_f32_e32 v47, v47, v49
	ds_write2_b32 v16, v40, v41 offset1:1
	ds_write2_b32 v16, v42, v43 offset0:2 offset1:3
	ds_write2_b32 v17, v44, v45 offset1:1
	ds_write2_b32 v17, v46, v47 offset0:2 offset1:3
	s_waitcnt lgkmcnt(0)
	s_barrier
	ds_read2_b32 v[76:77], v20 offset1:65
	ds_read2_b32 v[78:79], v20 offset0:130 offset1:195
	ds_read2_b32 v[80:81], v21 offset1:65
	ds_read2_b32 v[82:83], v21 offset0:130 offset1:195
	s_waitcnt lgkmcnt(0)
	v_cvt_pk_bf16_f32 v88, v76, v77
	v_cvt_pk_bf16_f32 v89, v78, v79
	v_cvt_pk_bf16_f32 v90, v80, v81
	v_cvt_pk_bf16_f32 v91, v82, v83
	global_store_dwordx4 v12, v[88:91], s[36:37]
	s_add_i32 s34, s46, 40
	s_lshr_b32 s42, s34, 4
	s_and_b32 s43, s34, 15
	s_lshl_b32 s44, s47, 22
	s_lshl_b32 s45, s43, 18
	s_add_u32 s44, s44, s45
	s_lshl_b32 s45, s42, 8
	s_add_u32 s44, s44, s45
	s_add_u32 s0, s88, s44
	s_addc_u32 s1, s89, 0
	global_load_dwordx4 v[40:43], v8, s[0:1]
	global_load_dwordx4 v[44:47], v9, s[0:1]
	s_waitcnt vmcnt(13)
	s_add_i32 s34, s46, 720
	s_lshr_b32 s42, s34, 4
	s_and_b32 s43, s34, 15
	s_mul_i32 s44, s47, 0x700000
	s_lshl_b32 s45, s42, 17
	s_add_u32 s44, s44, s45
	s_lshl_b32 s45, s43, 7
	s_add_u32 s44, s44, s45
	s_add_u32 s44, s44, 0x8000
	s_add_u32 s36, s70, s44
	s_addc_u32 s37, s71, 0
	v_mul_f32_e32 v52, v52, v60
	v_mul_f32_e32 v53, v53, v60
	v_mul_f32_e32 v54, v54, v60
	v_mul_f32_e32 v55, v55, v60
	v_mul_f32_e32 v56, v56, v61
	v_mul_f32_e32 v57, v57, v61
	v_mul_f32_e32 v58, v58, v61
	v_mul_f32_e32 v59, v59, v61
	ds_write2_b32 v14, v52, v53 offset1:1
	ds_write2_b32 v14, v54, v55 offset0:2 offset1:3
	ds_write2_b32 v15, v56, v57 offset1:1
	ds_write2_b32 v15, v58, v59 offset0:2 offset1:3
	s_waitcnt lgkmcnt(0)
	s_barrier
	ds_read2_b32 v[76:77], v18 offset1:65
	ds_read2_b32 v[78:79], v18 offset0:130 offset1:195
	ds_read2_b32 v[80:81], v19 offset1:65
	ds_read2_b32 v[82:83], v19 offset0:130 offset1:195
	s_waitcnt lgkmcnt(0)
	v_cvt_pk_bf16_f32 v84, v76, v77
	v_cvt_pk_bf16_f32 v85, v78, v79
	v_cvt_pk_bf16_f32 v86, v80, v81
	v_cvt_pk_bf16_f32 v87, v82, v83
	global_store_dwordx4 v12, v[84:87], s[36:37]
	s_add_i32 s34, s46, 112
	s_lshr_b32 s42, s34, 4
	s_and_b32 s43, s34, 15
	s_lshl_b32 s44, s47, 22
	s_lshl_b32 s45, s43, 18
	s_add_u32 s44, s44, s45
	s_lshl_b32 s45, s42, 8
	s_add_u32 s44, s44, s45
	s_add_u32 s0, s88, s44
	s_addc_u32 s1, s89, 0
	global_load_dwordx4 v[52:55], v8, s[0:1]
	global_load_dwordx4 v[56:59], v9, s[0:1]
	s_waitcnt vmcnt(11)
	s_add_i32 s34, s46, 792
	s_lshr_b32 s42, s34, 4
	s_and_b32 s43, s34, 15
	s_mul_i32 s44, s47, 0x700000
	s_lshl_b32 s45, s42, 17
	s_add_u32 s44, s44, s45
	s_lshl_b32 s45, s43, 7
	s_add_u32 s44, s44, s45
	s_add_u32 s44, s44, 0x8000
	s_add_u32 s36, s70, s44
	s_addc_u32 s37, s71, 0
	v_mul_f32_e32 v64, v64, v72
	v_mul_f32_e32 v65, v65, v72
	v_mul_f32_e32 v66, v66, v72
	v_mul_f32_e32 v67, v67, v72
	v_mul_f32_e32 v68, v68, v73
	v_mul_f32_e32 v69, v69, v73
	v_mul_f32_e32 v70, v70, v73
	v_mul_f32_e32 v71, v71, v73
	ds_write2_b32 v16, v64, v65 offset1:1
	ds_write2_b32 v16, v66, v67 offset0:2 offset1:3
	ds_write2_b32 v17, v68, v69 offset1:1
	ds_write2_b32 v17, v70, v71 offset0:2 offset1:3
	s_waitcnt lgkmcnt(0)
	s_barrier
	ds_read2_b32 v[76:77], v20 offset1:65
	ds_read2_b32 v[78:79], v20 offset0:130 offset1:195
	ds_read2_b32 v[80:81], v21 offset1:65
	ds_read2_b32 v[82:83], v21 offset0:130 offset1:195
	s_waitcnt lgkmcnt(0)
	v_cvt_pk_bf16_f32 v88, v76, v77
	v_cvt_pk_bf16_f32 v89, v78, v79
	v_cvt_pk_bf16_f32 v90, v80, v81
	v_cvt_pk_bf16_f32 v91, v82, v83
	global_store_dwordx4 v12, v[88:91], s[36:37]
	s_add_i32 s34, s46, 184
	s_lshr_b32 s42, s34, 4
	s_and_b32 s43, s34, 15
	s_lshl_b32 s44, s47, 22
	s_lshl_b32 s45, s43, 18
	s_add_u32 s44, s44, s45
	s_lshl_b32 s45, s42, 8
	s_add_u32 s44, s44, s45
	s_add_u32 s0, s88, s44
	s_addc_u32 s1, s89, 0
	global_load_dwordx4 v[64:67], v8, s[0:1]
	global_load_dwordx4 v[68:71], v9, s[0:1]
	s_waitcnt vmcnt(9)
	s_cmp_lt_u32 s46, 32
	s_cbranch_scc0 .Lconv_p12b
	s_add_i32 s34, s46, 864
	s_lshr_b32 s42, s34, 4
	s_and_b32 s43, s34, 15
	s_mul_i32 s44, s47, 0x700000
	s_lshl_b32 s45, s42, 17
	s_add_u32 s44, s44, s45
	s_lshl_b32 s45, s43, 7
	s_add_u32 s44, s44, s45
	s_add_u32 s44, s44, 0x8000
	s_add_u32 s36, s70, s44
	s_addc_u32 s37, s71, 0
	v_mul_f32_e32 v28, v28, v36
	v_mul_f32_e32 v29, v29, v36
	v_mul_f32_e32 v30, v30, v36
	v_mul_f32_e32 v31, v31, v36
	v_mul_f32_e32 v32, v32, v37
	v_mul_f32_e32 v33, v33, v37
	v_mul_f32_e32 v34, v34, v37
	v_mul_f32_e32 v35, v35, v37
	ds_write2_b32 v14, v28, v29 offset1:1
	ds_write2_b32 v14, v30, v31 offset0:2 offset1:3
	ds_write2_b32 v15, v32, v33 offset1:1
	ds_write2_b32 v15, v34, v35 offset0:2 offset1:3
	s_waitcnt lgkmcnt(0)
	s_barrier
	ds_read2_b32 v[76:77], v18 offset1:65
	ds_read2_b32 v[78:79], v18 offset0:130 offset1:195
	ds_read2_b32 v[80:81], v19 offset1:65
	ds_read2_b32 v[82:83], v19 offset0:130 offset1:195
	s_waitcnt lgkmcnt(0)
	v_cvt_pk_bf16_f32 v84, v76, v77
	v_cvt_pk_bf16_f32 v85, v78, v79
	v_cvt_pk_bf16_f32 v86, v80, v81
	v_cvt_pk_bf16_f32 v87, v82, v83
	global_store_dwordx4 v12, v[84:87], s[36:37]
	s_branch .Lconv_p12d
.Lconv_p12b:
	s_add_i32 s34, s46, -32
	s_lshr_b32 s42, s34, 4
	s_and_b32 s43, s34, 15
	s_lshl_b32 s44, s47, 21
	s_lshl_b32 s45, s42, 17
	s_add_u32 s44, s44, s45
	s_lshl_b32 s45, s43, 7
	s_add_u32 s44, s44, s45
	s_add_u32 s44, s44, 0x1c08000
	s_add_u32 s36, s70, s44
	s_addc_u32 s37, s71, 0
	ds_write2_b32 v14, v28, v29 offset1:1
	ds_write2_b32 v14, v30, v31 offset0:2 offset1:3
	ds_write2_b32 v15, v32, v33 offset1:1
	ds_write2_b32 v15, v34, v35 offset0:2 offset1:3
	s_waitcnt lgkmcnt(0)
	s_barrier
	ds_read2_b32 v[76:77], v18 offset1:65
	ds_read2_b32 v[78:79], v18 offset0:130 offset1:195
	ds_read2_b32 v[80:81], v19 offset1:65
	ds_read2_b32 v[82:83], v19 offset0:130 offset1:195
	s_waitcnt lgkmcnt(0)
	v_cvt_pk_bf16_f32 v84, v76, v77
	v_cvt_pk_bf16_f32 v85, v78, v79
	v_cvt_pk_bf16_f32 v86, v80, v81
	v_cvt_pk_bf16_f32 v87, v82, v83
	global_store_dwordx4 v12, v[84:87], s[36:37]
.Lconv_p12d:
	s_and_b32 s43, s46, 3
	s_lshl_b32 s44, s47, 16
	s_lshl_b32 s45, s43, 14
	s_add_u32 s44, s44, s45
	s_add_u32 s0, s84, s44
	s_addc_u32 s1, s85, 0
	s_lshl_b32 s44, s47, 10
	s_lshl_b32 s45, s43, 8
	s_add_u32 s44, s44, s45
	s_add_u32 s4, s86, s44
	s_addc_u32 s5, s87, 0
	global_load_dwordx4 v[28:31], v10, s[0:1]
	global_load_dwordx4 v[32:35], v11, s[0:1]
	global_load_dwordx4 v[36:39], v4, s[4:5]
	s_waitcnt vmcnt(10)
	s_add_i32 s34, s46, 40
	s_lshr_b32 s42, s34, 4
	s_and_b32 s43, s34, 15
	s_lshl_b32 s44, s47, 21
	s_lshl_b32 s45, s42, 17
	s_add_u32 s44, s44, s45
	s_lshl_b32 s45, s43, 7
	s_add_u32 s44, s44, s45
	s_add_u32 s44, s44, 0x1c08000
	s_add_u32 s36, s70, s44
	s_addc_u32 s37, s71, 0
	ds_write2_b32 v16, v40, v41 offset1:1
	ds_write2_b32 v16, v42, v43 offset0:2 offset1:3
	ds_write2_b32 v17, v44, v45 offset1:1
	ds_write2_b32 v17, v46, v47 offset0:2 offset1:3
	s_waitcnt lgkmcnt(0)
	s_barrier
	ds_read2_b32 v[76:77], v20 offset1:65
	ds_read2_b32 v[78:79], v20 offset0:130 offset1:195
	ds_read2_b32 v[80:81], v21 offset1:65
	ds_read2_b32 v[82:83], v21 offset0:130 offset1:195
	s_waitcnt lgkmcnt(0)
	v_cvt_pk_bf16_f32 v88, v76, v77
	v_cvt_pk_bf16_f32 v89, v78, v79
	v_cvt_pk_bf16_f32 v90, v80, v81
	v_cvt_pk_bf16_f32 v91, v82, v83
	global_store_dwordx4 v12, v[88:91], s[36:37]
	s_waitcnt vmcnt(8)
	s_add_i32 s34, s46, 112
	s_lshr_b32 s42, s34, 4
	s_and_b32 s43, s34, 15
	s_lshl_b32 s44, s47, 21
	s_lshl_b32 s45, s42, 17
	s_add_u32 s44, s44, s45
	s_lshl_b32 s45, s43, 7
	s_add_u32 s44, s44, s45
	s_add_u32 s44, s44, 0x1c08000
	s_add_u32 s36, s70, s44
	s_addc_u32 s37, s71, 0
	ds_write2_b32 v14, v52, v53 offset1:1
	ds_write2_b32 v14, v54, v55 offset0:2 offset1:3
	ds_write2_b32 v15, v56, v57 offset1:1
	ds_write2_b32 v15, v58, v59 offset0:2 offset1:3
	s_waitcnt lgkmcnt(0)
	s_barrier
	ds_read2_b32 v[76:77], v18 offset1:65
	ds_read2_b32 v[78:79], v18 offset0:130 offset1:195
	ds_read2_b32 v[80:81], v19 offset1:65
	ds_read2_b32 v[82:83], v19 offset0:130 offset1:195
	s_waitcnt lgkmcnt(0)
	v_cvt_pk_bf16_f32 v84, v76, v77
	v_cvt_pk_bf16_f32 v85, v78, v79
	v_cvt_pk_bf16_f32 v86, v80, v81
	v_cvt_pk_bf16_f32 v87, v82, v83
	global_store_dwordx4 v12, v[84:87], s[36:37]
	s_waitcnt vmcnt(6)
	s_add_i32 s34, s46, 184
	s_lshr_b32 s42, s34, 4
	s_and_b32 s43, s34, 15
	s_lshl_b32 s44, s47, 21
	s_lshl_b32 s45, s42, 17
	s_add_u32 s44, s44, s45
	s_lshl_b32 s45, s43, 7
	s_add_u32 s44, s44, s45
	s_add_u32 s44, s44, 0x1c08000
	s_add_u32 s36, s70, s44
	s_addc_u32 s37, s71, 0
	ds_write2_b32 v16, v64, v65 offset1:1
	ds_write2_b32 v16, v66, v67 offset0:2 offset1:3
	ds_write2_b32 v17, v68, v69 offset1:1
	ds_write2_b32 v17, v70, v71 offset0:2 offset1:3
	s_waitcnt lgkmcnt(0)
	s_barrier
	ds_read2_b32 v[76:77], v20 offset1:65
	ds_read2_b32 v[78:79], v20 offset0:130 offset1:195
	ds_read2_b32 v[80:81], v21 offset1:65
	ds_read2_b32 v[82:83], v21 offset0:130 offset1:195
	s_waitcnt lgkmcnt(0)
	v_cvt_pk_bf16_f32 v88, v76, v77
	v_cvt_pk_bf16_f32 v89, v78, v79
	v_cvt_pk_bf16_f32 v90, v80, v81
	v_cvt_pk_bf16_f32 v91, v82, v83
	global_store_dwordx4 v12, v[88:91], s[36:37]
	s_waitcnt vmcnt(3)
	s_cmp_lt_u32 s46, 4
	s_cbranch_scc0 .Lconv_done
	s_lshl_b32 s44, s47, 15
	s_lshl_b32 s45, s46, 13
	s_add_u32 s44, s44, s45
	s_add_u32 s44, s44, 0x2408000
	s_add_u32 s36, s70, s44
	s_addc_u32 s37, s71, 0
	v_mul_f32_e32 v28, v28, v36
	v_mul_f32_e32 v29, v29, v37
	v_mul_f32_e32 v30, v30, v38
	v_mul_f32_e32 v31, v31, v39
	v_mul_f32_e32 v32, v32, v36
	v_mul_f32_e32 v33, v33, v37
	v_mul_f32_e32 v34, v34, v38
	v_mul_f32_e32 v35, v35, v39
	ds_write2_b32 v14, v28, v29 offset1:1
	ds_write2_b32 v14, v30, v31 offset0:2 offset1:3
	ds_write2_b32 v15, v32, v33 offset1:1
	ds_write2_b32 v15, v34, v35 offset0:2 offset1:3
	s_waitcnt lgkmcnt(0)
	s_barrier
	ds_read2_b32 v[76:77], v18 offset1:65
	ds_read2_b32 v[78:79], v18 offset0:130 offset1:195
	ds_read2_b32 v[80:81], v19 offset1:65
	ds_read2_b32 v[82:83], v19 offset0:130 offset1:195
	s_waitcnt lgkmcnt(0)
	v_cvt_pk_bf16_f32 v84, v76, v77
	v_cvt_pk_bf16_f32 v85, v78, v79
	v_cvt_pk_bf16_f32 v86, v80, v81
	v_cvt_pk_bf16_f32 v87, v82, v83
	global_store_dwordx4 v13, v[84:87], s[36:37]
.Lconv_done:
	s_waitcnt vmcnt(0)
	s_mov_b64 s[38:39], exec
	s_branch .LBB0_29
